# S5 stage 1 hand-written: 16-block 4x4x4 bf16 MFMA B-projection directly in lane=state layout, no LDS transposition
# speedup vs baseline: 1.0025x; 1.0025x over previous
.LBB0_1147:
	s_cmp_lt_i32 s94, 7
	s_cselect_b64 s[2:3], -1, 0
	s_add_u32 s4, s92, 0x25e00000
	s_addc_u32 s5, s93, 0
	v_writelane_b32 v242, s4, 0
	s_nop 1
	v_writelane_b32 v242, s5, 1
	s_add_u32 s4, s92, 0x28e00000
	s_addc_u32 s5, s93, 0
	s_and_b64 s[18:19], s[2:3], s[0:1]
	v_writelane_b32 v242, s4, 4
	s_andn2_b64 vcc, exec, s[18:19]
	s_nop 0
	v_writelane_b32 v242, s5, 5
	s_cbranch_vccnz .LBB0_1333
	v_readlane_b32 s0, v243, 60
	s_cmpk_gt_i32 s0, 0x5fff
	v_and_b32_e32 v140, 15, v174
	v_and_b32_e32 v48, 48, v174
	v_readlane_b32 s1, v243, 61
	s_cbranch_scc1 .LBB0_1191
	v_readlane_b32 s4, v243, 60
	v_readlane_b32 s2, v243, 48
	v_readlane_b32 s3, v243, 49
	v_and_b32_e32 v49, 3, v172
	v_lshlrev_b32_e32 v60, 5, v172
	v_mov_b32_e32 v61, 0
	s_nop 1
	v_lshl_add_u64 v[60:61], s[2:3], 0, v[60:61]
	v_readlane_b32 s2, v242, 4
	v_readlane_b32 s3, v242, 5
	v_lshlrev_b32_e32 v62, 3, v172
	v_mov_b32_e32 v63, 0
	s_nop 1
	v_lshl_add_u64 v[62:63], s[2:3], 0, v[62:63]
	v_readlane_b32 s2, v243, 40
	s_mov_b32 s1, 0
.Ls5a_item:
	s_and_b32 s5, s4, 63
	s_and_b32 s6, s4, 0xffffffc0
	v_or_b32_e32 v50, s6, v49
	v_lshlrev_b32_e32 v50, 11, v50
	s_lshl_b32 s0, s5, 5
	v_add_u32_e32 v50, s0, v50
	s_lshl_b32 s0, s5, 9
	v_lshl_add_u32 v51, v172, 3, s0
	global_load_dwordx2 v[2:3], v51, s[92:93]
	s_lshl_b32 s0, s5, 12
	v_lshl_add_u64 v[232:233], v[60:61], 0, s[0:1]
	global_load_dwordx4 v[4:7], v[232:233], off
	global_load_dwordx4 v[8:11], v[232:233], off offset:16
	global_load_dwordx4 v[12:15], v[232:233], off offset:2048
	global_load_dwordx4 v[16:19], v[232:233], off offset:2064
	global_load_dwordx4 v[64:67], v50, s[60:61]
	global_load_dwordx4 v[68:71], v50, s[60:61] offset:16
	v_add_u32_e32 v235, 0x2000, v50
	global_load_dwordx4 v[72:75], v235, s[60:61]
	global_load_dwordx4 v[76:79], v235, s[60:61] offset:16
	v_add_u32_e32 v236, 0x4000, v50
	global_load_dwordx4 v[80:83], v236, s[60:61]
	global_load_dwordx4 v[84:87], v236, s[60:61] offset:16
	v_add_u32_e32 v237, 0x6000, v50
	global_load_dwordx4 v[88:91], v237, s[60:61]
	global_load_dwordx4 v[92:95], v237, s[60:61] offset:16
	v_add_u32_e32 v234, 0x8000, v50
	global_load_dwordx4 v[96:99], v234, s[60:61]
	global_load_dwordx4 v[100:103], v234, s[60:61] offset:16
	v_add_u32_e32 v235, 0xa000, v50
	global_load_dwordx4 v[104:107], v235, s[60:61]
	global_load_dwordx4 v[108:111], v235, s[60:61] offset:16
	v_add_u32_e32 v236, 0xc000, v50
	global_load_dwordx4 v[112:115], v236, s[60:61]
	global_load_dwordx4 v[116:119], v236, s[60:61] offset:16
	v_add_u32_e32 v237, 0xe000, v50
	global_load_dwordx4 v[120:123], v237, s[60:61]
	global_load_dwordx4 v[124:127], v237, s[60:61] offset:16
	v_add_u32_e32 v234, 0x10000, v50
	global_load_dwordx4 v[128:131], v234, s[60:61]
	global_load_dwordx4 v[132:135], v234, s[60:61] offset:16
	v_add_u32_e32 v235, 0x12000, v50
	global_load_dwordx4 v[142:145], v235, s[60:61]
	global_load_dwordx4 v[146:149], v235, s[60:61] offset:16
	v_add_u32_e32 v236, 0x14000, v50
	global_load_dwordx4 v[150:153], v236, s[60:61]
	global_load_dwordx4 v[154:157], v236, s[60:61] offset:16
	v_add_u32_e32 v237, 0x16000, v50
	global_load_dwordx4 v[158:161], v237, s[60:61]
	global_load_dwordx4 v[162:165], v237, s[60:61] offset:16
	v_add_u32_e32 v234, 0x18000, v50
	global_load_dwordx4 v[176:179], v234, s[60:61]
	global_load_dwordx4 v[180:183], v234, s[60:61] offset:16
	v_add_u32_e32 v235, 0x1a000, v50
	global_load_dwordx4 v[184:187], v235, s[60:61]
	global_load_dwordx4 v[188:191], v235, s[60:61] offset:16
	v_add_u32_e32 v236, 0x1c000, v50
	global_load_dwordx4 v[200:203], v236, s[60:61]
	global_load_dwordx4 v[204:207], v236, s[60:61] offset:16
	v_add_u32_e32 v237, 0x1e000, v50
	global_load_dwordx4 v[208:211], v237, s[60:61]
	global_load_dwordx4 v[212:215], v237, s[60:61] offset:16
	s_lshl_b32 s0, s5, 9
	s_add_i32 s0, s0, 0x8000
	v_lshl_add_u32 v51, v172, 3, s0
	global_load_dwordx2 v[36:37], v51, s[92:93]
	s_lshl_b32 s0, s5, 12
	s_add_i32 s0, s0, 0x40000
	v_lshl_add_u64 v[232:233], v[60:61], 0, s[0:1]
	global_load_dwordx4 v[38:41], v[232:233], off
	global_load_dwordx4 v[42:45], v[232:233], off offset:16
	global_load_dwordx4 v[52:55], v[232:233], off offset:2048
	global_load_dwordx4 v[56:59], v[232:233], off offset:2064
	v_mov_b32_e32 v0, 0
	v_mov_b32_e32 v1, 0
	s_waitcnt vmcnt(33)
	v_mfma_f32_4x4x4_16b_bf16 v[20:23], v[64:65], v[4:5], 0
	v_mfma_f32_4x4x4_16b_bf16 v[24:27], v[64:65], v[12:13], 0
	v_mfma_f32_4x4x4_16b_bf16 v[28:31], v[72:73], v[4:5], 0
	v_mfma_f32_4x4x4_16b_bf16 v[32:35], v[72:73], v[12:13], 0
	v_mfma_f32_4x4x4_16b_bf16 v[20:23], v[66:67], v[6:7], v[20:23]
	v_mfma_f32_4x4x4_16b_bf16 v[24:27], v[66:67], v[14:15], v[24:27]
	v_mfma_f32_4x4x4_16b_bf16 v[28:31], v[74:75], v[6:7], v[28:31]
	v_mfma_f32_4x4x4_16b_bf16 v[32:35], v[74:75], v[14:15], v[32:35]
	v_mfma_f32_4x4x4_16b_bf16 v[20:23], v[68:69], v[8:9], v[20:23]
	v_mfma_f32_4x4x4_16b_bf16 v[24:27], v[68:69], v[16:17], v[24:27]
	v_mfma_f32_4x4x4_16b_bf16 v[28:31], v[76:77], v[8:9], v[28:31]
	v_mfma_f32_4x4x4_16b_bf16 v[32:35], v[76:77], v[16:17], v[32:35]
	v_mfma_f32_4x4x4_16b_bf16 v[20:23], v[70:71], v[10:11], v[20:23]
	v_mfma_f32_4x4x4_16b_bf16 v[24:27], v[70:71], v[18:19], v[24:27]
	v_mfma_f32_4x4x4_16b_bf16 v[28:31], v[78:79], v[10:11], v[28:31]
	v_mfma_f32_4x4x4_16b_bf16 v[32:35], v[78:79], v[18:19], v[32:35]
	s_waitcnt vmcnt(29)
	v_mfma_f32_4x4x4_16b_bf16 v[216:219], v[80:81], v[4:5], 0
	v_mfma_f32_4x4x4_16b_bf16 v[220:223], v[80:81], v[12:13], 0
	v_mfma_f32_4x4x4_16b_bf16 v[224:227], v[88:89], v[4:5], 0
	v_mfma_f32_4x4x4_16b_bf16 v[228:231], v[88:89], v[12:13], 0
	v_mfma_f32_4x4x4_16b_bf16 v[216:219], v[82:83], v[6:7], v[216:219]
	v_mfma_f32_4x4x4_16b_bf16 v[220:223], v[82:83], v[14:15], v[220:223]
	v_mfma_f32_4x4x4_16b_bf16 v[224:227], v[90:91], v[6:7], v[224:227]
	v_mfma_f32_4x4x4_16b_bf16 v[228:231], v[90:91], v[14:15], v[228:231]
	v_mfma_f32_4x4x4_16b_bf16 v[216:219], v[84:85], v[8:9], v[216:219]
	v_mfma_f32_4x4x4_16b_bf16 v[220:223], v[84:85], v[16:17], v[220:223]
	v_mfma_f32_4x4x4_16b_bf16 v[224:227], v[92:93], v[8:9], v[224:227]
	v_mfma_f32_4x4x4_16b_bf16 v[228:231], v[92:93], v[16:17], v[228:231]
	v_mfma_f32_4x4x4_16b_bf16 v[216:219], v[86:87], v[10:11], v[216:219]
	v_mfma_f32_4x4x4_16b_bf16 v[220:223], v[86:87], v[18:19], v[220:223]
	v_mfma_f32_4x4x4_16b_bf16 v[224:227], v[94:95], v[10:11], v[224:227]
	v_mfma_f32_4x4x4_16b_bf16 v[228:231], v[94:95], v[18:19], v[228:231]
	v_fma_f32 v46, -v3, v1, v20
	v_fma_f32 v47, v3, v0, v24
	v_fmac_f32_e32 v46, v2, v0
	v_fmac_f32_e32 v47, v2, v1
	v_fma_f32 v0, -v3, v47, v21
	v_fma_f32 v1, v3, v46, v25
	v_fmac_f32_e32 v0, v2, v46
	v_fmac_f32_e32 v1, v2, v47
	v_fma_f32 v46, -v3, v1, v22
	v_fma_f32 v47, v3, v0, v26
	v_fmac_f32_e32 v46, v2, v0
	v_fmac_f32_e32 v47, v2, v1
	v_fma_f32 v0, -v3, v47, v23
	v_fma_f32 v1, v3, v46, v27
	v_fmac_f32_e32 v0, v2, v46
	v_fmac_f32_e32 v1, v2, v47
	v_fma_f32 v46, -v3, v1, v28
	v_fma_f32 v47, v3, v0, v32
	v_fmac_f32_e32 v46, v2, v0
	v_fmac_f32_e32 v47, v2, v1
	v_fma_f32 v0, -v3, v47, v29
	v_fma_f32 v1, v3, v46, v33
	v_fmac_f32_e32 v0, v2, v46
	v_fmac_f32_e32 v1, v2, v47
	v_fma_f32 v46, -v3, v1, v30
	v_fma_f32 v47, v3, v0, v34
	v_fmac_f32_e32 v46, v2, v0
	v_fmac_f32_e32 v47, v2, v1
	v_fma_f32 v0, -v3, v47, v31
	v_fma_f32 v1, v3, v46, v35
	v_fmac_f32_e32 v0, v2, v46
	v_fmac_f32_e32 v1, v2, v47
	s_waitcnt vmcnt(25)
	v_mfma_f32_4x4x4_16b_bf16 v[20:23], v[96:97], v[4:5], 0
	v_mfma_f32_4x4x4_16b_bf16 v[24:27], v[96:97], v[12:13], 0
	v_mfma_f32_4x4x4_16b_bf16 v[28:31], v[104:105], v[4:5], 0
	v_mfma_f32_4x4x4_16b_bf16 v[32:35], v[104:105], v[12:13], 0
	v_mfma_f32_4x4x4_16b_bf16 v[20:23], v[98:99], v[6:7], v[20:23]
	v_mfma_f32_4x4x4_16b_bf16 v[24:27], v[98:99], v[14:15], v[24:27]
	v_mfma_f32_4x4x4_16b_bf16 v[28:31], v[106:107], v[6:7], v[28:31]
	v_mfma_f32_4x4x4_16b_bf16 v[32:35], v[106:107], v[14:15], v[32:35]
	v_mfma_f32_4x4x4_16b_bf16 v[20:23], v[100:101], v[8:9], v[20:23]
	v_mfma_f32_4x4x4_16b_bf16 v[24:27], v[100:101], v[16:17], v[24:27]
	v_mfma_f32_4x4x4_16b_bf16 v[28:31], v[108:109], v[8:9], v[28:31]
	v_mfma_f32_4x4x4_16b_bf16 v[32:35], v[108:109], v[16:17], v[32:35]
	v_mfma_f32_4x4x4_16b_bf16 v[20:23], v[102:103], v[10:11], v[20:23]
	v_mfma_f32_4x4x4_16b_bf16 v[24:27], v[102:103], v[18:19], v[24:27]
	v_mfma_f32_4x4x4_16b_bf16 v[28:31], v[110:111], v[10:11], v[28:31]
	v_mfma_f32_4x4x4_16b_bf16 v[32:35], v[110:111], v[18:19], v[32:35]
	v_fma_f32 v46, -v3, v1, v216
	v_fma_f32 v47, v3, v0, v220
	v_fmac_f32_e32 v46, v2, v0
	v_fmac_f32_e32 v47, v2, v1
	v_fma_f32 v0, -v3, v47, v217
	v_fma_f32 v1, v3, v46, v221
	v_fmac_f32_e32 v0, v2, v46
	v_fmac_f32_e32 v1, v2, v47
	v_fma_f32 v46, -v3, v1, v218
	v_fma_f32 v47, v3, v0, v222
	v_fmac_f32_e32 v46, v2, v0
	v_fmac_f32_e32 v47, v2, v1
	v_fma_f32 v0, -v3, v47, v219
	v_fma_f32 v1, v3, v46, v223
	v_fmac_f32_e32 v0, v2, v46
	v_fmac_f32_e32 v1, v2, v47
	v_fma_f32 v46, -v3, v1, v224
	v_fma_f32 v47, v3, v0, v228
	v_fmac_f32_e32 v46, v2, v0
	v_fmac_f32_e32 v47, v2, v1
	v_fma_f32 v0, -v3, v47, v225
	v_fma_f32 v1, v3, v46, v229
	v_fmac_f32_e32 v0, v2, v46
	v_fmac_f32_e32 v1, v2, v47
	v_fma_f32 v46, -v3, v1, v226
	v_fma_f32 v47, v3, v0, v230
	v_fmac_f32_e32 v46, v2, v0
	v_fmac_f32_e32 v47, v2, v1
	v_fma_f32 v0, -v3, v47, v227
	v_fma_f32 v1, v3, v46, v231
	v_fmac_f32_e32 v0, v2, v46
	v_fmac_f32_e32 v1, v2, v47
	s_waitcnt vmcnt(21)
	v_mfma_f32_4x4x4_16b_bf16 v[216:219], v[112:113], v[4:5], 0
	v_mfma_f32_4x4x4_16b_bf16 v[220:223], v[112:113], v[12:13], 0
	v_mfma_f32_4x4x4_16b_bf16 v[224:227], v[120:121], v[4:5], 0
	v_mfma_f32_4x4x4_16b_bf16 v[228:231], v[120:121], v[12:13], 0
	v_mfma_f32_4x4x4_16b_bf16 v[216:219], v[114:115], v[6:7], v[216:219]
	v_mfma_f32_4x4x4_16b_bf16 v[220:223], v[114:115], v[14:15], v[220:223]
	v_mfma_f32_4x4x4_16b_bf16 v[224:227], v[122:123], v[6:7], v[224:227]
	v_mfma_f32_4x4x4_16b_bf16 v[228:231], v[122:123], v[14:15], v[228:231]
	v_mfma_f32_4x4x4_16b_bf16 v[216:219], v[116:117], v[8:9], v[216:219]
	v_mfma_f32_4x4x4_16b_bf16 v[220:223], v[116:117], v[16:17], v[220:223]
	v_mfma_f32_4x4x4_16b_bf16 v[224:227], v[124:125], v[8:9], v[224:227]
	v_mfma_f32_4x4x4_16b_bf16 v[228:231], v[124:125], v[16:17], v[228:231]
	v_mfma_f32_4x4x4_16b_bf16 v[216:219], v[118:119], v[10:11], v[216:219]
	v_mfma_f32_4x4x4_16b_bf16 v[220:223], v[118:119], v[18:19], v[220:223]
	v_mfma_f32_4x4x4_16b_bf16 v[224:227], v[126:127], v[10:11], v[224:227]
	v_mfma_f32_4x4x4_16b_bf16 v[228:231], v[126:127], v[18:19], v[228:231]
	v_fma_f32 v46, -v3, v1, v20
	v_fma_f32 v47, v3, v0, v24
	v_fmac_f32_e32 v46, v2, v0
	v_fmac_f32_e32 v47, v2, v1
	v_fma_f32 v0, -v3, v47, v21
	v_fma_f32 v1, v3, v46, v25
	v_fmac_f32_e32 v0, v2, v46
	v_fmac_f32_e32 v1, v2, v47
	v_fma_f32 v46, -v3, v1, v22
	v_fma_f32 v47, v3, v0, v26
	v_fmac_f32_e32 v46, v2, v0
	v_fmac_f32_e32 v47, v2, v1
	v_fma_f32 v0, -v3, v47, v23
	v_fma_f32 v1, v3, v46, v27
	v_fmac_f32_e32 v0, v2, v46
	v_fmac_f32_e32 v1, v2, v47
	v_fma_f32 v46, -v3, v1, v28
	v_fma_f32 v47, v3, v0, v32
	v_fmac_f32_e32 v46, v2, v0
	v_fmac_f32_e32 v47, v2, v1
	v_fma_f32 v0, -v3, v47, v29
	v_fma_f32 v1, v3, v46, v33
	v_fmac_f32_e32 v0, v2, v46
	v_fmac_f32_e32 v1, v2, v47
	v_fma_f32 v46, -v3, v1, v30
	v_fma_f32 v47, v3, v0, v34
	v_fmac_f32_e32 v46, v2, v0
	v_fmac_f32_e32 v47, v2, v1
	v_fma_f32 v0, -v3, v47, v31
	v_fma_f32 v1, v3, v46, v35
	v_fmac_f32_e32 v0, v2, v46
	v_fmac_f32_e32 v1, v2, v47
	s_waitcnt vmcnt(17)
	v_mfma_f32_4x4x4_16b_bf16 v[20:23], v[128:129], v[4:5], 0
	v_mfma_f32_4x4x4_16b_bf16 v[24:27], v[128:129], v[12:13], 0
	v_mfma_f32_4x4x4_16b_bf16 v[28:31], v[142:143], v[4:5], 0
	v_mfma_f32_4x4x4_16b_bf16 v[32:35], v[142:143], v[12:13], 0
	v_mfma_f32_4x4x4_16b_bf16 v[20:23], v[130:131], v[6:7], v[20:23]
	v_mfma_f32_4x4x4_16b_bf16 v[24:27], v[130:131], v[14:15], v[24:27]
	v_mfma_f32_4x4x4_16b_bf16 v[28:31], v[144:145], v[6:7], v[28:31]
	v_mfma_f32_4x4x4_16b_bf16 v[32:35], v[144:145], v[14:15], v[32:35]
	v_mfma_f32_4x4x4_16b_bf16 v[20:23], v[132:133], v[8:9], v[20:23]
	v_mfma_f32_4x4x4_16b_bf16 v[24:27], v[132:133], v[16:17], v[24:27]
	v_mfma_f32_4x4x4_16b_bf16 v[28:31], v[146:147], v[8:9], v[28:31]
	v_mfma_f32_4x4x4_16b_bf16 v[32:35], v[146:147], v[16:17], v[32:35]
	v_mfma_f32_4x4x4_16b_bf16 v[20:23], v[134:135], v[10:11], v[20:23]
	v_mfma_f32_4x4x4_16b_bf16 v[24:27], v[134:135], v[18:19], v[24:27]
	v_mfma_f32_4x4x4_16b_bf16 v[28:31], v[148:149], v[10:11], v[28:31]
	v_mfma_f32_4x4x4_16b_bf16 v[32:35], v[148:149], v[18:19], v[32:35]
	v_fma_f32 v46, -v3, v1, v216
	v_fma_f32 v47, v3, v0, v220
	v_fmac_f32_e32 v46, v2, v0
	v_fmac_f32_e32 v47, v2, v1
	v_fma_f32 v0, -v3, v47, v217
	v_fma_f32 v1, v3, v46, v221
	v_fmac_f32_e32 v0, v2, v46
	v_fmac_f32_e32 v1, v2, v47
	v_fma_f32 v46, -v3, v1, v218
	v_fma_f32 v47, v3, v0, v222
	v_fmac_f32_e32 v46, v2, v0
	v_fmac_f32_e32 v47, v2, v1
	v_fma_f32 v0, -v3, v47, v219
	v_fma_f32 v1, v3, v46, v223
	v_fmac_f32_e32 v0, v2, v46
	v_fmac_f32_e32 v1, v2, v47
	v_fma_f32 v46, -v3, v1, v224
	v_fma_f32 v47, v3, v0, v228
	v_fmac_f32_e32 v46, v2, v0
	v_fmac_f32_e32 v47, v2, v1
	v_fma_f32 v0, -v3, v47, v225
	v_fma_f32 v1, v3, v46, v229
	v_fmac_f32_e32 v0, v2, v46
	v_fmac_f32_e32 v1, v2, v47
	v_fma_f32 v46, -v3, v1, v226
	v_fma_f32 v47, v3, v0, v230
	v_fmac_f32_e32 v46, v2, v0
	v_fmac_f32_e32 v47, v2, v1
	v_fma_f32 v0, -v3, v47, v227
	v_fma_f32 v1, v3, v46, v231
	v_fmac_f32_e32 v0, v2, v46
	v_fmac_f32_e32 v1, v2, v47
	s_waitcnt vmcnt(13)
	v_mfma_f32_4x4x4_16b_bf16 v[216:219], v[150:151], v[4:5], 0
	v_mfma_f32_4x4x4_16b_bf16 v[220:223], v[150:151], v[12:13], 0
	v_mfma_f32_4x4x4_16b_bf16 v[224:227], v[158:159], v[4:5], 0
	v_mfma_f32_4x4x4_16b_bf16 v[228:231], v[158:159], v[12:13], 0
	v_mfma_f32_4x4x4_16b_bf16 v[216:219], v[152:153], v[6:7], v[216:219]
	v_mfma_f32_4x4x4_16b_bf16 v[220:223], v[152:153], v[14:15], v[220:223]
	v_mfma_f32_4x4x4_16b_bf16 v[224:227], v[160:161], v[6:7], v[224:227]
	v_mfma_f32_4x4x4_16b_bf16 v[228:231], v[160:161], v[14:15], v[228:231]
	v_mfma_f32_4x4x4_16b_bf16 v[216:219], v[154:155], v[8:9], v[216:219]
	v_mfma_f32_4x4x4_16b_bf16 v[220:223], v[154:155], v[16:17], v[220:223]
	v_mfma_f32_4x4x4_16b_bf16 v[224:227], v[162:163], v[8:9], v[224:227]
	v_mfma_f32_4x4x4_16b_bf16 v[228:231], v[162:163], v[16:17], v[228:231]
	v_mfma_f32_4x4x4_16b_bf16 v[216:219], v[156:157], v[10:11], v[216:219]
	v_mfma_f32_4x4x4_16b_bf16 v[220:223], v[156:157], v[18:19], v[220:223]
	v_mfma_f32_4x4x4_16b_bf16 v[224:227], v[164:165], v[10:11], v[224:227]
	v_mfma_f32_4x4x4_16b_bf16 v[228:231], v[164:165], v[18:19], v[228:231]
	v_fma_f32 v46, -v3, v1, v20
	v_fma_f32 v47, v3, v0, v24
	v_fmac_f32_e32 v46, v2, v0
	v_fmac_f32_e32 v47, v2, v1
	v_fma_f32 v0, -v3, v47, v21
	v_fma_f32 v1, v3, v46, v25
	v_fmac_f32_e32 v0, v2, v46
	v_fmac_f32_e32 v1, v2, v47
	v_fma_f32 v46, -v3, v1, v22
	v_fma_f32 v47, v3, v0, v26
	v_fmac_f32_e32 v46, v2, v0
	v_fmac_f32_e32 v47, v2, v1
	v_fma_f32 v0, -v3, v47, v23
	v_fma_f32 v1, v3, v46, v27
	v_fmac_f32_e32 v0, v2, v46
	v_fmac_f32_e32 v1, v2, v47
	v_fma_f32 v46, -v3, v1, v28
	v_fma_f32 v47, v3, v0, v32
	v_fmac_f32_e32 v46, v2, v0
	v_fmac_f32_e32 v47, v2, v1
	v_fma_f32 v0, -v3, v47, v29
	v_fma_f32 v1, v3, v46, v33
	v_fmac_f32_e32 v0, v2, v46
	v_fmac_f32_e32 v1, v2, v47
	v_fma_f32 v46, -v3, v1, v30
	v_fma_f32 v47, v3, v0, v34
	v_fmac_f32_e32 v46, v2, v0
	v_fmac_f32_e32 v47, v2, v1
	v_fma_f32 v0, -v3, v47, v31
	v_fma_f32 v1, v3, v46, v35
	v_fmac_f32_e32 v0, v2, v46
	v_fmac_f32_e32 v1, v2, v47
	s_waitcnt vmcnt(9)
	v_mfma_f32_4x4x4_16b_bf16 v[20:23], v[176:177], v[4:5], 0
	v_mfma_f32_4x4x4_16b_bf16 v[24:27], v[176:177], v[12:13], 0
	v_mfma_f32_4x4x4_16b_bf16 v[28:31], v[184:185], v[4:5], 0
	v_mfma_f32_4x4x4_16b_bf16 v[32:35], v[184:185], v[12:13], 0
	v_mfma_f32_4x4x4_16b_bf16 v[20:23], v[178:179], v[6:7], v[20:23]
	v_mfma_f32_4x4x4_16b_bf16 v[24:27], v[178:179], v[14:15], v[24:27]
	v_mfma_f32_4x4x4_16b_bf16 v[28:31], v[186:187], v[6:7], v[28:31]
	v_mfma_f32_4x4x4_16b_bf16 v[32:35], v[186:187], v[14:15], v[32:35]
	v_mfma_f32_4x4x4_16b_bf16 v[20:23], v[180:181], v[8:9], v[20:23]
	v_mfma_f32_4x4x4_16b_bf16 v[24:27], v[180:181], v[16:17], v[24:27]
	v_mfma_f32_4x4x4_16b_bf16 v[28:31], v[188:189], v[8:9], v[28:31]
	v_mfma_f32_4x4x4_16b_bf16 v[32:35], v[188:189], v[16:17], v[32:35]
	v_mfma_f32_4x4x4_16b_bf16 v[20:23], v[182:183], v[10:11], v[20:23]
	v_mfma_f32_4x4x4_16b_bf16 v[24:27], v[182:183], v[18:19], v[24:27]
	v_mfma_f32_4x4x4_16b_bf16 v[28:31], v[190:191], v[10:11], v[28:31]
	v_mfma_f32_4x4x4_16b_bf16 v[32:35], v[190:191], v[18:19], v[32:35]
	v_fma_f32 v46, -v3, v1, v216
	v_fma_f32 v47, v3, v0, v220
	v_fmac_f32_e32 v46, v2, v0
	v_fmac_f32_e32 v47, v2, v1
	v_fma_f32 v0, -v3, v47, v217
	v_fma_f32 v1, v3, v46, v221
	v_fmac_f32_e32 v0, v2, v46
	v_fmac_f32_e32 v1, v2, v47
	v_fma_f32 v46, -v3, v1, v218
	v_fma_f32 v47, v3, v0, v222
	v_fmac_f32_e32 v46, v2, v0
	v_fmac_f32_e32 v47, v2, v1
	v_fma_f32 v0, -v3, v47, v219
	v_fma_f32 v1, v3, v46, v223
	v_fmac_f32_e32 v0, v2, v46
	v_fmac_f32_e32 v1, v2, v47
	v_fma_f32 v46, -v3, v1, v224
	v_fma_f32 v47, v3, v0, v228
	v_fmac_f32_e32 v46, v2, v0
	v_fmac_f32_e32 v47, v2, v1
	v_fma_f32 v0, -v3, v47, v225
	v_fma_f32 v1, v3, v46, v229
	v_fmac_f32_e32 v0, v2, v46
	v_fmac_f32_e32 v1, v2, v47
	v_fma_f32 v46, -v3, v1, v226
	v_fma_f32 v47, v3, v0, v230
	v_fmac_f32_e32 v46, v2, v0
	v_fmac_f32_e32 v47, v2, v1
	v_fma_f32 v0, -v3, v47, v227
	v_fma_f32 v1, v3, v46, v231
	v_fmac_f32_e32 v0, v2, v46
	v_fmac_f32_e32 v1, v2, v47
	s_waitcnt vmcnt(5)
	v_mfma_f32_4x4x4_16b_bf16 v[216:219], v[200:201], v[4:5], 0
	v_mfma_f32_4x4x4_16b_bf16 v[220:223], v[200:201], v[12:13], 0
	v_mfma_f32_4x4x4_16b_bf16 v[224:227], v[208:209], v[4:5], 0
	v_mfma_f32_4x4x4_16b_bf16 v[228:231], v[208:209], v[12:13], 0
	v_mfma_f32_4x4x4_16b_bf16 v[216:219], v[202:203], v[6:7], v[216:219]
	v_mfma_f32_4x4x4_16b_bf16 v[220:223], v[202:203], v[14:15], v[220:223]
	v_mfma_f32_4x4x4_16b_bf16 v[224:227], v[210:211], v[6:7], v[224:227]
	v_mfma_f32_4x4x4_16b_bf16 v[228:231], v[210:211], v[14:15], v[228:231]
	v_mfma_f32_4x4x4_16b_bf16 v[216:219], v[204:205], v[8:9], v[216:219]
	v_mfma_f32_4x4x4_16b_bf16 v[220:223], v[204:205], v[16:17], v[220:223]
	v_mfma_f32_4x4x4_16b_bf16 v[224:227], v[212:213], v[8:9], v[224:227]
	v_mfma_f32_4x4x4_16b_bf16 v[228:231], v[212:213], v[16:17], v[228:231]
	v_mfma_f32_4x4x4_16b_bf16 v[216:219], v[206:207], v[10:11], v[216:219]
	v_mfma_f32_4x4x4_16b_bf16 v[220:223], v[206:207], v[18:19], v[220:223]
	v_mfma_f32_4x4x4_16b_bf16 v[224:227], v[214:215], v[10:11], v[224:227]
	v_mfma_f32_4x4x4_16b_bf16 v[228:231], v[214:215], v[18:19], v[228:231]
	v_fma_f32 v46, -v3, v1, v20
	v_fma_f32 v47, v3, v0, v24
	v_fmac_f32_e32 v46, v2, v0
	v_fmac_f32_e32 v47, v2, v1
	v_fma_f32 v0, -v3, v47, v21
	v_fma_f32 v1, v3, v46, v25
	v_fmac_f32_e32 v0, v2, v46
	v_fmac_f32_e32 v1, v2, v47
	v_fma_f32 v46, -v3, v1, v22
	v_fma_f32 v47, v3, v0, v26
	v_fmac_f32_e32 v46, v2, v0
	v_fmac_f32_e32 v47, v2, v1
	v_fma_f32 v0, -v3, v47, v23
	v_fma_f32 v1, v3, v46, v27
	v_fmac_f32_e32 v0, v2, v46
	v_fmac_f32_e32 v1, v2, v47
	v_fma_f32 v46, -v3, v1, v28
	v_fma_f32 v47, v3, v0, v32
	v_fmac_f32_e32 v46, v2, v0
	v_fmac_f32_e32 v47, v2, v1
	v_fma_f32 v0, -v3, v47, v29
	v_fma_f32 v1, v3, v46, v33
	v_fmac_f32_e32 v0, v2, v46
	v_fmac_f32_e32 v1, v2, v47
	v_fma_f32 v46, -v3, v1, v30
	v_fma_f32 v47, v3, v0, v34
	v_fmac_f32_e32 v46, v2, v0
	v_fmac_f32_e32 v47, v2, v1
	v_fma_f32 v0, -v3, v47, v31
	v_fma_f32 v1, v3, v46, v35
	v_fmac_f32_e32 v0, v2, v46
	v_fmac_f32_e32 v1, v2, v47
	s_nop 4
	v_fma_f32 v46, -v3, v1, v216
	v_fma_f32 v47, v3, v0, v220
	v_fmac_f32_e32 v46, v2, v0
	v_fmac_f32_e32 v47, v2, v1
	v_fma_f32 v0, -v3, v47, v217
	v_fma_f32 v1, v3, v46, v221
	v_fmac_f32_e32 v0, v2, v46
	v_fmac_f32_e32 v1, v2, v47
	v_fma_f32 v46, -v3, v1, v218
	v_fma_f32 v47, v3, v0, v222
	v_fmac_f32_e32 v46, v2, v0
	v_fmac_f32_e32 v47, v2, v1
	v_fma_f32 v0, -v3, v47, v219
	v_fma_f32 v1, v3, v46, v223
	v_fmac_f32_e32 v0, v2, v46
	v_fmac_f32_e32 v1, v2, v47
	v_fma_f32 v46, -v3, v1, v224
	v_fma_f32 v47, v3, v0, v228
	v_fmac_f32_e32 v46, v2, v0
	v_fmac_f32_e32 v47, v2, v1
	v_fma_f32 v0, -v3, v47, v225
	v_fma_f32 v1, v3, v46, v229
	v_fmac_f32_e32 v0, v2, v46
	v_fmac_f32_e32 v1, v2, v47
	v_fma_f32 v46, -v3, v1, v226
	v_fma_f32 v47, v3, v0, v230
	v_fmac_f32_e32 v46, v2, v0
	v_fmac_f32_e32 v47, v2, v1
	v_fma_f32 v0, -v3, v47, v227
	v_fma_f32 v1, v3, v46, v231
	v_fmac_f32_e32 v0, v2, v46
	v_fmac_f32_e32 v1, v2, v47
	s_lshl_b32 s0, s6, 10
	s_lshl_b32 s3, s5, 9
	s_add_i32 s0, s0, s3
	v_lshl_add_u64 v[232:233], v[62:63], 0, s[0:1]
	s_waitcnt vmcnt(0)
	global_store_dwordx2 v[232:233], v[0:1], off
	s_waitcnt vmcnt(0)
	v_mov_b32_e32 v0, 0
	v_mov_b32_e32 v1, 0
	v_mfma_f32_4x4x4_16b_bf16 v[20:23], v[208:209], v[38:39], 0
	v_mfma_f32_4x4x4_16b_bf16 v[24:27], v[208:209], v[52:53], 0
	v_mfma_f32_4x4x4_16b_bf16 v[28:31], v[200:201], v[38:39], 0
	v_mfma_f32_4x4x4_16b_bf16 v[32:35], v[200:201], v[52:53], 0
	v_mfma_f32_4x4x4_16b_bf16 v[20:23], v[210:211], v[40:41], v[20:23]
	v_mfma_f32_4x4x4_16b_bf16 v[24:27], v[210:211], v[54:55], v[24:27]
	v_mfma_f32_4x4x4_16b_bf16 v[28:31], v[202:203], v[40:41], v[28:31]
	v_mfma_f32_4x4x4_16b_bf16 v[32:35], v[202:203], v[54:55], v[32:35]
	v_mfma_f32_4x4x4_16b_bf16 v[20:23], v[212:213], v[42:43], v[20:23]
	v_mfma_f32_4x4x4_16b_bf16 v[24:27], v[212:213], v[56:57], v[24:27]
	v_mfma_f32_4x4x4_16b_bf16 v[28:31], v[204:205], v[42:43], v[28:31]
	v_mfma_f32_4x4x4_16b_bf16 v[32:35], v[204:205], v[56:57], v[32:35]
	v_mfma_f32_4x4x4_16b_bf16 v[20:23], v[214:215], v[44:45], v[20:23]
	v_mfma_f32_4x4x4_16b_bf16 v[24:27], v[214:215], v[58:59], v[24:27]
	v_mfma_f32_4x4x4_16b_bf16 v[28:31], v[206:207], v[44:45], v[28:31]
	v_mfma_f32_4x4x4_16b_bf16 v[32:35], v[206:207], v[58:59], v[32:35]
	v_mfma_f32_4x4x4_16b_bf16 v[216:219], v[184:185], v[38:39], 0
	v_mfma_f32_4x4x4_16b_bf16 v[220:223], v[184:185], v[52:53], 0
	v_mfma_f32_4x4x4_16b_bf16 v[224:227], v[176:177], v[38:39], 0
	v_mfma_f32_4x4x4_16b_bf16 v[228:231], v[176:177], v[52:53], 0
	v_mfma_f32_4x4x4_16b_bf16 v[216:219], v[186:187], v[40:41], v[216:219]
	v_mfma_f32_4x4x4_16b_bf16 v[220:223], v[186:187], v[54:55], v[220:223]
	v_mfma_f32_4x4x4_16b_bf16 v[224:227], v[178:179], v[40:41], v[224:227]
	v_mfma_f32_4x4x4_16b_bf16 v[228:231], v[178:179], v[54:55], v[228:231]
	v_mfma_f32_4x4x4_16b_bf16 v[216:219], v[188:189], v[42:43], v[216:219]
	v_mfma_f32_4x4x4_16b_bf16 v[220:223], v[188:189], v[56:57], v[220:223]
	v_mfma_f32_4x4x4_16b_bf16 v[224:227], v[180:181], v[42:43], v[224:227]
	v_mfma_f32_4x4x4_16b_bf16 v[228:231], v[180:181], v[56:57], v[228:231]
	v_mfma_f32_4x4x4_16b_bf16 v[216:219], v[190:191], v[44:45], v[216:219]
	v_mfma_f32_4x4x4_16b_bf16 v[220:223], v[190:191], v[58:59], v[220:223]
	v_mfma_f32_4x4x4_16b_bf16 v[224:227], v[182:183], v[44:45], v[224:227]
	v_mfma_f32_4x4x4_16b_bf16 v[228:231], v[182:183], v[58:59], v[228:231]
	v_fma_f32 v46, -v37, v1, v23
	v_fma_f32 v47, v37, v0, v27
	v_fmac_f32_e32 v46, v36, v0
	v_fmac_f32_e32 v47, v36, v1
	v_fma_f32 v0, -v37, v47, v22
	v_fma_f32 v1, v37, v46, v26
	v_fmac_f32_e32 v0, v36, v46
	v_fmac_f32_e32 v1, v36, v47
	v_fma_f32 v46, -v37, v1, v21
	v_fma_f32 v47, v37, v0, v25
	v_fmac_f32_e32 v46, v36, v0
	v_fmac_f32_e32 v47, v36, v1
	v_fma_f32 v0, -v37, v47, v20
	v_fma_f32 v1, v37, v46, v24
	v_fmac_f32_e32 v0, v36, v46
	v_fmac_f32_e32 v1, v36, v47
	v_fma_f32 v46, -v37, v1, v31
	v_fma_f32 v47, v37, v0, v35
	v_fmac_f32_e32 v46, v36, v0
	v_fmac_f32_e32 v47, v36, v1
	v_fma_f32 v0, -v37, v47, v30
	v_fma_f32 v1, v37, v46, v34
	v_fmac_f32_e32 v0, v36, v46
	v_fmac_f32_e32 v1, v36, v47
	v_fma_f32 v46, -v37, v1, v29
	v_fma_f32 v47, v37, v0, v33
	v_fmac_f32_e32 v46, v36, v0
	v_fmac_f32_e32 v47, v36, v1
	v_fma_f32 v0, -v37, v47, v28
	v_fma_f32 v1, v37, v46, v32
	v_fmac_f32_e32 v0, v36, v46
	v_fmac_f32_e32 v1, v36, v47
	v_mfma_f32_4x4x4_16b_bf16 v[20:23], v[158:159], v[38:39], 0
	v_mfma_f32_4x4x4_16b_bf16 v[24:27], v[158:159], v[52:53], 0
	v_mfma_f32_4x4x4_16b_bf16 v[28:31], v[150:151], v[38:39], 0
	v_mfma_f32_4x4x4_16b_bf16 v[32:35], v[150:151], v[52:53], 0
	v_mfma_f32_4x4x4_16b_bf16 v[20:23], v[160:161], v[40:41], v[20:23]
	v_mfma_f32_4x4x4_16b_bf16 v[24:27], v[160:161], v[54:55], v[24:27]
	v_mfma_f32_4x4x4_16b_bf16 v[28:31], v[152:153], v[40:41], v[28:31]
	v_mfma_f32_4x4x4_16b_bf16 v[32:35], v[152:153], v[54:55], v[32:35]
	v_mfma_f32_4x4x4_16b_bf16 v[20:23], v[162:163], v[42:43], v[20:23]
	v_mfma_f32_4x4x4_16b_bf16 v[24:27], v[162:163], v[56:57], v[24:27]
	v_mfma_f32_4x4x4_16b_bf16 v[28:31], v[154:155], v[42:43], v[28:31]
	v_mfma_f32_4x4x4_16b_bf16 v[32:35], v[154:155], v[56:57], v[32:35]
	v_mfma_f32_4x4x4_16b_bf16 v[20:23], v[164:165], v[44:45], v[20:23]
	v_mfma_f32_4x4x4_16b_bf16 v[24:27], v[164:165], v[58:59], v[24:27]
	v_mfma_f32_4x4x4_16b_bf16 v[28:31], v[156:157], v[44:45], v[28:31]
	v_mfma_f32_4x4x4_16b_bf16 v[32:35], v[156:157], v[58:59], v[32:35]
	v_fma_f32 v46, -v37, v1, v219
	v_fma_f32 v47, v37, v0, v223
	v_fmac_f32_e32 v46, v36, v0
	v_fmac_f32_e32 v47, v36, v1
	v_fma_f32 v0, -v37, v47, v218
	v_fma_f32 v1, v37, v46, v222
	v_fmac_f32_e32 v0, v36, v46
	v_fmac_f32_e32 v1, v36, v47
	v_fma_f32 v46, -v37, v1, v217
	v_fma_f32 v47, v37, v0, v221
	v_fmac_f32_e32 v46, v36, v0
	v_fmac_f32_e32 v47, v36, v1
	v_fma_f32 v0, -v37, v47, v216
	v_fma_f32 v1, v37, v46, v220
	v_fmac_f32_e32 v0, v36, v46
	v_fmac_f32_e32 v1, v36, v47
	v_fma_f32 v46, -v37, v1, v227
	v_fma_f32 v47, v37, v0, v231
	v_fmac_f32_e32 v46, v36, v0
	v_fmac_f32_e32 v47, v36, v1
	v_fma_f32 v0, -v37, v47, v226
	v_fma_f32 v1, v37, v46, v230
	v_fmac_f32_e32 v0, v36, v46
	v_fmac_f32_e32 v1, v36, v47
	v_fma_f32 v46, -v37, v1, v225
	v_fma_f32 v47, v37, v0, v229
	v_fmac_f32_e32 v46, v36, v0
	v_fmac_f32_e32 v47, v36, v1
	v_fma_f32 v0, -v37, v47, v224
	v_fma_f32 v1, v37, v46, v228
	v_fmac_f32_e32 v0, v36, v46
	v_fmac_f32_e32 v1, v36, v47
	v_mfma_f32_4x4x4_16b_bf16 v[216:219], v[142:143], v[38:39], 0
	v_mfma_f32_4x4x4_16b_bf16 v[220:223], v[142:143], v[52:53], 0
	v_mfma_f32_4x4x4_16b_bf16 v[224:227], v[128:129], v[38:39], 0
	v_mfma_f32_4x4x4_16b_bf16 v[228:231], v[128:129], v[52:53], 0
	v_mfma_f32_4x4x4_16b_bf16 v[216:219], v[144:145], v[40:41], v[216:219]
	v_mfma_f32_4x4x4_16b_bf16 v[220:223], v[144:145], v[54:55], v[220:223]
	v_mfma_f32_4x4x4_16b_bf16 v[224:227], v[130:131], v[40:41], v[224:227]
	v_mfma_f32_4x4x4_16b_bf16 v[228:231], v[130:131], v[54:55], v[228:231]
	v_mfma_f32_4x4x4_16b_bf16 v[216:219], v[146:147], v[42:43], v[216:219]
	v_mfma_f32_4x4x4_16b_bf16 v[220:223], v[146:147], v[56:57], v[220:223]
	v_mfma_f32_4x4x4_16b_bf16 v[224:227], v[132:133], v[42:43], v[224:227]
	v_mfma_f32_4x4x4_16b_bf16 v[228:231], v[132:133], v[56:57], v[228:231]
	v_mfma_f32_4x4x4_16b_bf16 v[216:219], v[148:149], v[44:45], v[216:219]
	v_mfma_f32_4x4x4_16b_bf16 v[220:223], v[148:149], v[58:59], v[220:223]
	v_mfma_f32_4x4x4_16b_bf16 v[224:227], v[134:135], v[44:45], v[224:227]
	v_mfma_f32_4x4x4_16b_bf16 v[228:231], v[134:135], v[58:59], v[228:231]
	v_fma_f32 v46, -v37, v1, v23
	v_fma_f32 v47, v37, v0, v27
	v_fmac_f32_e32 v46, v36, v0
	v_fmac_f32_e32 v47, v36, v1
	v_fma_f32 v0, -v37, v47, v22
	v_fma_f32 v1, v37, v46, v26
	v_fmac_f32_e32 v0, v36, v46
	v_fmac_f32_e32 v1, v36, v47
	v_fma_f32 v46, -v37, v1, v21
	v_fma_f32 v47, v37, v0, v25
	v_fmac_f32_e32 v46, v36, v0
	v_fmac_f32_e32 v47, v36, v1
	v_fma_f32 v0, -v37, v47, v20
	v_fma_f32 v1, v37, v46, v24
	v_fmac_f32_e32 v0, v36, v46
	v_fmac_f32_e32 v1, v36, v47
	v_fma_f32 v46, -v37, v1, v31
	v_fma_f32 v47, v37, v0, v35
	v_fmac_f32_e32 v46, v36, v0
	v_fmac_f32_e32 v47, v36, v1
	v_fma_f32 v0, -v37, v47, v30
	v_fma_f32 v1, v37, v46, v34
	v_fmac_f32_e32 v0, v36, v46
	v_fmac_f32_e32 v1, v36, v47
	v_fma_f32 v46, -v37, v1, v29
	v_fma_f32 v47, v37, v0, v33
	v_fmac_f32_e32 v46, v36, v0
	v_fmac_f32_e32 v47, v36, v1
	v_fma_f32 v0, -v37, v47, v28
	v_fma_f32 v1, v37, v46, v32
	v_fmac_f32_e32 v0, v36, v46
	v_fmac_f32_e32 v1, v36, v47
	v_mfma_f32_4x4x4_16b_bf16 v[20:23], v[120:121], v[38:39], 0
	v_mfma_f32_4x4x4_16b_bf16 v[24:27], v[120:121], v[52:53], 0
	v_mfma_f32_4x4x4_16b_bf16 v[28:31], v[112:113], v[38:39], 0
	v_mfma_f32_4x4x4_16b_bf16 v[32:35], v[112:113], v[52:53], 0
	v_mfma_f32_4x4x4_16b_bf16 v[20:23], v[122:123], v[40:41], v[20:23]
	v_mfma_f32_4x4x4_16b_bf16 v[24:27], v[122:123], v[54:55], v[24:27]
	v_mfma_f32_4x4x4_16b_bf16 v[28:31], v[114:115], v[40:41], v[28:31]
	v_mfma_f32_4x4x4_16b_bf16 v[32:35], v[114:115], v[54:55], v[32:35]
	v_mfma_f32_4x4x4_16b_bf16 v[20:23], v[124:125], v[42:43], v[20:23]
	v_mfma_f32_4x4x4_16b_bf16 v[24:27], v[124:125], v[56:57], v[24:27]
	v_mfma_f32_4x4x4_16b_bf16 v[28:31], v[116:117], v[42:43], v[28:31]
	v_mfma_f32_4x4x4_16b_bf16 v[32:35], v[116:117], v[56:57], v[32:35]
	v_mfma_f32_4x4x4_16b_bf16 v[20:23], v[126:127], v[44:45], v[20:23]
	v_mfma_f32_4x4x4_16b_bf16 v[24:27], v[126:127], v[58:59], v[24:27]
	v_mfma_f32_4x4x4_16b_bf16 v[28:31], v[118:119], v[44:45], v[28:31]
	v_mfma_f32_4x4x4_16b_bf16 v[32:35], v[118:119], v[58:59], v[32:35]
	v_fma_f32 v46, -v37, v1, v219
	v_fma_f32 v47, v37, v0, v223
	v_fmac_f32_e32 v46, v36, v0
	v_fmac_f32_e32 v47, v36, v1
	v_fma_f32 v0, -v37, v47, v218
	v_fma_f32 v1, v37, v46, v222
	v_fmac_f32_e32 v0, v36, v46
	v_fmac_f32_e32 v1, v36, v47
	v_fma_f32 v46, -v37, v1, v217
	v_fma_f32 v47, v37, v0, v221
	v_fmac_f32_e32 v46, v36, v0
	v_fmac_f32_e32 v47, v36, v1
	v_fma_f32 v0, -v37, v47, v216
	v_fma_f32 v1, v37, v46, v220
	v_fmac_f32_e32 v0, v36, v46
	v_fmac_f32_e32 v1, v36, v47
	v_fma_f32 v46, -v37, v1, v227
	v_fma_f32 v47, v37, v0, v231
	v_fmac_f32_e32 v46, v36, v0
	v_fmac_f32_e32 v47, v36, v1
	v_fma_f32 v0, -v37, v47, v226
	v_fma_f32 v1, v37, v46, v230
	v_fmac_f32_e32 v0, v36, v46
	v_fmac_f32_e32 v1, v36, v47
	v_fma_f32 v46, -v37, v1, v225
	v_fma_f32 v47, v37, v0, v229
	v_fmac_f32_e32 v46, v36, v0
	v_fmac_f32_e32 v47, v36, v1
	v_fma_f32 v0, -v37, v47, v224
	v_fma_f32 v1, v37, v46, v228
	v_fmac_f32_e32 v0, v36, v46
	v_fmac_f32_e32 v1, v36, v47
	v_mfma_f32_4x4x4_16b_bf16 v[216:219], v[104:105], v[38:39], 0
	v_mfma_f32_4x4x4_16b_bf16 v[220:223], v[104:105], v[52:53], 0
	v_mfma_f32_4x4x4_16b_bf16 v[224:227], v[96:97], v[38:39], 0
	v_mfma_f32_4x4x4_16b_bf16 v[228:231], v[96:97], v[52:53], 0
	v_mfma_f32_4x4x4_16b_bf16 v[216:219], v[106:107], v[40:41], v[216:219]
	v_mfma_f32_4x4x4_16b_bf16 v[220:223], v[106:107], v[54:55], v[220:223]
	v_mfma_f32_4x4x4_16b_bf16 v[224:227], v[98:99], v[40:41], v[224:227]
	v_mfma_f32_4x4x4_16b_bf16 v[228:231], v[98:99], v[54:55], v[228:231]
	v_mfma_f32_4x4x4_16b_bf16 v[216:219], v[108:109], v[42:43], v[216:219]
	v_mfma_f32_4x4x4_16b_bf16 v[220:223], v[108:109], v[56:57], v[220:223]
	v_mfma_f32_4x4x4_16b_bf16 v[224:227], v[100:101], v[42:43], v[224:227]
	v_mfma_f32_4x4x4_16b_bf16 v[228:231], v[100:101], v[56:57], v[228:231]
	v_mfma_f32_4x4x4_16b_bf16 v[216:219], v[110:111], v[44:45], v[216:219]
	v_mfma_f32_4x4x4_16b_bf16 v[220:223], v[110:111], v[58:59], v[220:223]
	v_mfma_f32_4x4x4_16b_bf16 v[224:227], v[102:103], v[44:45], v[224:227]
	v_mfma_f32_4x4x4_16b_bf16 v[228:231], v[102:103], v[58:59], v[228:231]
	v_fma_f32 v46, -v37, v1, v23
	v_fma_f32 v47, v37, v0, v27
	v_fmac_f32_e32 v46, v36, v0
	v_fmac_f32_e32 v47, v36, v1
	v_fma_f32 v0, -v37, v47, v22
	v_fma_f32 v1, v37, v46, v26
	v_fmac_f32_e32 v0, v36, v46
	v_fmac_f32_e32 v1, v36, v47
	v_fma_f32 v46, -v37, v1, v21
	v_fma_f32 v47, v37, v0, v25
	v_fmac_f32_e32 v46, v36, v0
	v_fmac_f32_e32 v47, v36, v1
	v_fma_f32 v0, -v37, v47, v20
	v_fma_f32 v1, v37, v46, v24
	v_fmac_f32_e32 v0, v36, v46
	v_fmac_f32_e32 v1, v36, v47
	v_fma_f32 v46, -v37, v1, v31
	v_fma_f32 v47, v37, v0, v35
	v_fmac_f32_e32 v46, v36, v0
	v_fmac_f32_e32 v47, v36, v1
	v_fma_f32 v0, -v37, v47, v30
	v_fma_f32 v1, v37, v46, v34
	v_fmac_f32_e32 v0, v36, v46
	v_fmac_f32_e32 v1, v36, v47
	v_fma_f32 v46, -v37, v1, v29
	v_fma_f32 v47, v37, v0, v33
	v_fmac_f32_e32 v46, v36, v0
	v_fmac_f32_e32 v47, v36, v1
	v_fma_f32 v0, -v37, v47, v28
	v_fma_f32 v1, v37, v46, v32
	v_fmac_f32_e32 v0, v36, v46
	v_fmac_f32_e32 v1, v36, v47
	v_mfma_f32_4x4x4_16b_bf16 v[20:23], v[88:89], v[38:39], 0
	v_mfma_f32_4x4x4_16b_bf16 v[24:27], v[88:89], v[52:53], 0
	v_mfma_f32_4x4x4_16b_bf16 v[28:31], v[80:81], v[38:39], 0
	v_mfma_f32_4x4x4_16b_bf16 v[32:35], v[80:81], v[52:53], 0
	v_mfma_f32_4x4x4_16b_bf16 v[20:23], v[90:91], v[40:41], v[20:23]
	v_mfma_f32_4x4x4_16b_bf16 v[24:27], v[90:91], v[54:55], v[24:27]
	v_mfma_f32_4x4x4_16b_bf16 v[28:31], v[82:83], v[40:41], v[28:31]
	v_mfma_f32_4x4x4_16b_bf16 v[32:35], v[82:83], v[54:55], v[32:35]
	v_mfma_f32_4x4x4_16b_bf16 v[20:23], v[92:93], v[42:43], v[20:23]
	v_mfma_f32_4x4x4_16b_bf16 v[24:27], v[92:93], v[56:57], v[24:27]
	v_mfma_f32_4x4x4_16b_bf16 v[28:31], v[84:85], v[42:43], v[28:31]
	v_mfma_f32_4x4x4_16b_bf16 v[32:35], v[84:85], v[56:57], v[32:35]
	v_mfma_f32_4x4x4_16b_bf16 v[20:23], v[94:95], v[44:45], v[20:23]
	v_mfma_f32_4x4x4_16b_bf16 v[24:27], v[94:95], v[58:59], v[24:27]
	v_mfma_f32_4x4x4_16b_bf16 v[28:31], v[86:87], v[44:45], v[28:31]
	v_mfma_f32_4x4x4_16b_bf16 v[32:35], v[86:87], v[58:59], v[32:35]
	v_fma_f32 v46, -v37, v1, v219
	v_fma_f32 v47, v37, v0, v223
	v_fmac_f32_e32 v46, v36, v0
	v_fmac_f32_e32 v47, v36, v1
	v_fma_f32 v0, -v37, v47, v218
	v_fma_f32 v1, v37, v46, v222
	v_fmac_f32_e32 v0, v36, v46
	v_fmac_f32_e32 v1, v36, v47
	v_fma_f32 v46, -v37, v1, v217
	v_fma_f32 v47, v37, v0, v221
	v_fmac_f32_e32 v46, v36, v0
	v_fmac_f32_e32 v47, v36, v1
	v_fma_f32 v0, -v37, v47, v216
	v_fma_f32 v1, v37, v46, v220
	v_fmac_f32_e32 v0, v36, v46
	v_fmac_f32_e32 v1, v36, v47
	v_fma_f32 v46, -v37, v1, v227
	v_fma_f32 v47, v37, v0, v231
	v_fmac_f32_e32 v46, v36, v0
	v_fmac_f32_e32 v47, v36, v1
	v_fma_f32 v0, -v37, v47, v226
	v_fma_f32 v1, v37, v46, v230
	v_fmac_f32_e32 v0, v36, v46
	v_fmac_f32_e32 v1, v36, v47
	v_fma_f32 v46, -v37, v1, v225
	v_fma_f32 v47, v37, v0, v229
	v_fmac_f32_e32 v46, v36, v0
	v_fmac_f32_e32 v47, v36, v1
	v_fma_f32 v0, -v37, v47, v224
	v_fma_f32 v1, v37, v46, v228
	v_fmac_f32_e32 v0, v36, v46
	v_fmac_f32_e32 v1, v36, v47
	v_mfma_f32_4x4x4_16b_bf16 v[216:219], v[72:73], v[38:39], 0
	v_mfma_f32_4x4x4_16b_bf16 v[220:223], v[72:73], v[52:53], 0
	v_mfma_f32_4x4x4_16b_bf16 v[224:227], v[64:65], v[38:39], 0
	v_mfma_f32_4x4x4_16b_bf16 v[228:231], v[64:65], v[52:53], 0
	v_mfma_f32_4x4x4_16b_bf16 v[216:219], v[74:75], v[40:41], v[216:219]
	v_mfma_f32_4x4x4_16b_bf16 v[220:223], v[74:75], v[54:55], v[220:223]
	v_mfma_f32_4x4x4_16b_bf16 v[224:227], v[66:67], v[40:41], v[224:227]
	v_mfma_f32_4x4x4_16b_bf16 v[228:231], v[66:67], v[54:55], v[228:231]
	v_mfma_f32_4x4x4_16b_bf16 v[216:219], v[76:77], v[42:43], v[216:219]
	v_mfma_f32_4x4x4_16b_bf16 v[220:223], v[76:77], v[56:57], v[220:223]
	v_mfma_f32_4x4x4_16b_bf16 v[224:227], v[68:69], v[42:43], v[224:227]
	v_mfma_f32_4x4x4_16b_bf16 v[228:231], v[68:69], v[56:57], v[228:231]
	v_mfma_f32_4x4x4_16b_bf16 v[216:219], v[78:79], v[44:45], v[216:219]
	v_mfma_f32_4x4x4_16b_bf16 v[220:223], v[78:79], v[58:59], v[220:223]
	v_mfma_f32_4x4x4_16b_bf16 v[224:227], v[70:71], v[44:45], v[224:227]
	v_mfma_f32_4x4x4_16b_bf16 v[228:231], v[70:71], v[58:59], v[228:231]
	v_fma_f32 v46, -v37, v1, v23
	v_fma_f32 v47, v37, v0, v27
	v_fmac_f32_e32 v46, v36, v0
	v_fmac_f32_e32 v47, v36, v1
	v_fma_f32 v0, -v37, v47, v22
	v_fma_f32 v1, v37, v46, v26
	v_fmac_f32_e32 v0, v36, v46
	v_fmac_f32_e32 v1, v36, v47
	v_fma_f32 v46, -v37, v1, v21
	v_fma_f32 v47, v37, v0, v25
	v_fmac_f32_e32 v46, v36, v0
	v_fmac_f32_e32 v47, v36, v1
	v_fma_f32 v0, -v37, v47, v20
	v_fma_f32 v1, v37, v46, v24
	v_fmac_f32_e32 v0, v36, v46
	v_fmac_f32_e32 v1, v36, v47
	v_fma_f32 v46, -v37, v1, v31
	v_fma_f32 v47, v37, v0, v35
	v_fmac_f32_e32 v46, v36, v0
	v_fmac_f32_e32 v47, v36, v1
	v_fma_f32 v0, -v37, v47, v30
	v_fma_f32 v1, v37, v46, v34
	v_fmac_f32_e32 v0, v36, v46
	v_fmac_f32_e32 v1, v36, v47
	v_fma_f32 v46, -v37, v1, v29
	v_fma_f32 v47, v37, v0, v33
	v_fmac_f32_e32 v46, v36, v0
	v_fmac_f32_e32 v47, v36, v1
	v_fma_f32 v0, -v37, v47, v28
	v_fma_f32 v1, v37, v46, v32
	v_fmac_f32_e32 v0, v36, v46
	v_fmac_f32_e32 v1, v36, v47
	s_nop 4
	v_fma_f32 v46, -v37, v1, v219
	v_fma_f32 v47, v37, v0, v223
	v_fmac_f32_e32 v46, v36, v0
	v_fmac_f32_e32 v47, v36, v1
	v_fma_f32 v0, -v37, v47, v218
	v_fma_f32 v1, v37, v46, v222
	v_fmac_f32_e32 v0, v36, v46
	v_fmac_f32_e32 v1, v36, v47
	v_fma_f32 v46, -v37, v1, v217
	v_fma_f32 v47, v37, v0, v221
	v_fmac_f32_e32 v46, v36, v0
	v_fmac_f32_e32 v47, v36, v1
	v_fma_f32 v0, -v37, v47, v216
	v_fma_f32 v1, v37, v46, v220
	v_fmac_f32_e32 v0, v36, v46
	v_fmac_f32_e32 v1, v36, v47
	v_fma_f32 v46, -v37, v1, v227
	v_fma_f32 v47, v37, v0, v231
	v_fmac_f32_e32 v46, v36, v0
	v_fmac_f32_e32 v47, v36, v1
	v_fma_f32 v0, -v37, v47, v226
	v_fma_f32 v1, v37, v46, v230
	v_fmac_f32_e32 v0, v36, v46
	v_fmac_f32_e32 v1, v36, v47
	v_fma_f32 v46, -v37, v1, v225
	v_fma_f32 v47, v37, v0, v229
	v_fmac_f32_e32 v46, v36, v0
	v_fmac_f32_e32 v47, v36, v1
	v_fma_f32 v0, -v37, v47, v224
	v_fma_f32 v1, v37, v46, v228
	v_fmac_f32_e32 v0, v36, v46
	v_fmac_f32_e32 v1, v36, v47
	s_lshl_b32 s0, s6, 10
	s_lshl_b32 s3, s5, 9
	s_add_i32 s0, s0, s3
	s_add_i32 s0, s0, 0x8000
	v_lshl_add_u64 v[232:233], v[62:63], 0, s[0:1]
	global_store_dwordx2 v[232:233], v[0:1], off
	s_add_i32 s4, s4, s2
	s_cmpk_gt_i32 s4, 0x5fff
	s_cbranch_scc0 .Ls5a_item
